# panel exchanges without the invalidate: partial records and X tiles are written sc1 and read with sc1 loads, so the consumer needs no L1/L2 invalidate after the arrival count
# speedup vs baseline: 1.0042x; 1.0042x over previous
.LBB0_1252:
	global_load_dword v1, v0, s[18:19] sc1
	s_mov_b64 s[20:21], -1
	s_waitcnt vmcnt(0)
	v_cmp_lt_u32_e32 vcc, 3, v1
	s_cbranch_vccnz .LBB0_1251
	s_sleep 2
	global_load_dword v1, v0, s[18:19] sc1
	s_waitcnt vmcnt(0)
	v_cmp_gt_u32_e32 vcc, 4, v1
	s_cbranch_vccz .LBB0_1251
	s_sleep 2
	global_load_dword v1, v0, s[18:19] sc1
	s_waitcnt vmcnt(0)
	v_cmp_gt_u32_e32 vcc, 4, v1
	s_cbranch_vccz .LBB0_1251
	s_sleep 2
	global_load_dword v1, v0, s[18:19] sc1
	s_waitcnt vmcnt(0)
	v_cmp_gt_u32_e32 vcc, 4, v1
	s_cbranch_vccz .LBB0_1251
	s_sleep 2
	global_load_dword v1, v0, s[18:19] sc1
	s_waitcnt vmcnt(0)
	v_cmp_gt_u32_e32 vcc, 4, v1
	s_cbranch_vccz .LBB0_1251
	s_add_i32 s5, s5, -5
	s_cmp_eq_u32 s5, 0
	s_cselect_b64 s[20:21], -1, 0
	s_sleep 2
	s_branch .LBB0_1251
.LBB0_1258:
	s_waitcnt vmcnt(0)
.LBB0_1259:
	s_or_b64 exec, exec, s[10:11]
	s_sext_i32_i8 s5, s26
	s_lshl_b32 s4, s4, 8
	s_lshl_b32 s10, s5, 6
	v_mov_b32_e32 v1, v170
	s_waitcnt lgkmcnt(0)
	s_barrier
	s_load_dwordx2 s[52:53], s[0:1], 0xe8
	s_add_i32 s66, s4, s10
	v_readfirstlane_b32 s65, v170
	v_and_b32_e32 v226, 63, v170
	v_mov_b32_e32 v228, 0x358637bd
	v_lshlrev_b32_e32 v227, 3, v226
	v_lshlrev_b32_e32 v226, 4, v226
	s_lshr_b32 s65, s65, 6
	s_add_i32 s66, s66, s65
	s_waitcnt lgkmcnt(0)
	s_sub_i32 s67, s66, 0x1000
	s_ashr_i32 s67, s67, 11
	s_add_i32 s67, s67, 1
	s_cmp_gt_i32 s66, 0xfff
	s_cselect_b32 s67, s67, 0
	s_add_i32 s67, s67, 0
	s_mul_i32 s67, s67, 6
	s_add_i32 s67, s67, 3
	s_lshl_b32 s67, s67, 12
	s_add_u32 s58, s52, 0x780000
	s_addc_u32 s59, s53, 0
	s_add_u32 s58, s58, s67
	s_addc_u32 s59, s59, 0
	s_add_u32 s60, s58, 0x1000
	s_addc_u32 s61, s59, 0
	global_load_dwordx4 v[178:181], v226, s[58:59]
	global_load_dwordx4 v[182:185], v226, s[58:59] offset:1024
	global_load_dwordx4 v[186:189], v226, s[58:59] offset:2048
	global_load_dwordx4 v[190:193], v226, s[58:59] offset:3072
	global_load_dwordx4 v[194:197], v226, s[60:61]
	global_load_dwordx4 v[198:201], v226, s[60:61] offset:1024
	global_load_dwordx4 v[202:205], v226, s[60:61] offset:2048
	global_load_dwordx4 v[206:209], v226, s[60:61] offset:3072
	s_lshl_b32 s67, s66, 11
	s_add_u32 s56, s52, 0x2ebc000
	s_addc_u32 s57, s53, 0
	s_add_u32 s56, s56, s67
	s_addc_u32 s57, s57, 0
	s_lshl_b32 s67, s66, 12
	s_add_u32 s54, s52, 0x46bc000
	s_addc_u32 s55, s53, 0
	s_add_u32 s54, s54, s67
	s_addc_u32 s55, s55, 0
	global_load_dwordx4 v[0:3], v226, s[54:55] sc1
	global_load_dwordx4 v[4:7], v226, s[54:55] offset:1024 sc1
	global_load_dwordx4 v[8:11], v226, s[54:55] offset:2048 sc1
	global_load_dwordx4 v[12:15], v226, s[54:55] offset:3072 sc1
	s_add_u32 s54, s54, 0x8000
	s_addc_u32 s55, s55, 0
	global_load_dwordx4 v[16:19], v226, s[54:55] sc1
	global_load_dwordx4 v[20:23], v226, s[54:55] offset:1024 sc1
	global_load_dwordx4 v[24:27], v226, s[54:55] offset:2048 sc1
	global_load_dwordx4 v[28:31], v226, s[54:55] offset:3072 sc1
	s_add_u32 s54, s54, 0x8000
	s_addc_u32 s55, s55, 0
	global_load_dwordx4 v[32:35], v226, s[54:55] sc1
	global_load_dwordx4 v[36:39], v226, s[54:55] offset:1024 sc1
	global_load_dwordx4 v[40:43], v226, s[54:55] offset:2048 sc1
	global_load_dwordx4 v[44:47], v226, s[54:55] offset:3072 sc1
	s_add_u32 s54, s54, 0x8000
	s_addc_u32 s55, s55, 0
	global_load_dwordx4 v[48:51], v226, s[54:55] sc1
	global_load_dwordx4 v[52:55], v226, s[54:55] offset:1024 sc1
	global_load_dwordx4 v[56:59], v226, s[54:55] offset:2048 sc1
	global_load_dwordx4 v[60:63], v226, s[54:55] offset:3072 sc1
	s_add_u32 s54, s54, 0x8000
	s_addc_u32 s55, s55, 0
	global_load_dwordx4 v[64:67], v226, s[54:55] sc1
	global_load_dwordx4 v[68:71], v226, s[54:55] offset:1024 sc1
	global_load_dwordx4 v[72:75], v226, s[54:55] offset:2048 sc1
	global_load_dwordx4 v[76:79], v226, s[54:55] offset:3072 sc1
	s_add_u32 s54, s54, 0x8000
	s_addc_u32 s55, s55, 0
	global_load_dwordx4 v[80:83], v226, s[54:55] sc1
	global_load_dwordx4 v[84:87], v226, s[54:55] offset:1024 sc1
	global_load_dwordx4 v[88:91], v226, s[54:55] offset:2048 sc1
	global_load_dwordx4 v[92:95], v226, s[54:55] offset:3072 sc1
	s_add_u32 s54, s54, 0x8000
	s_addc_u32 s55, s55, 0
	global_load_dwordx4 v[134:137], v226, s[54:55] sc1
	global_load_dwordx4 v[138:141], v226, s[54:55] offset:1024 sc1
	global_load_dwordx4 v[142:145], v226, s[54:55] offset:2048 sc1
	global_load_dwordx4 v[146:149], v226, s[54:55] offset:3072 sc1
	s_add_u32 s54, s54, 0x8000
	s_addc_u32 s55, s55, 0
	global_load_dwordx4 v[150:153], v226, s[54:55] sc1
	global_load_dwordx4 v[154:157], v226, s[54:55] offset:1024 sc1
	global_load_dwordx4 v[158:161], v226, s[54:55] offset:2048 sc1
	global_load_dwordx4 v[162:165], v226, s[54:55] offset:3072 sc1
	s_waitcnt vmcnt(28)
	v_mul_f32_e32 v210, v0, v0
	v_fmac_f32_e32 v210, v1, v1
	v_fmac_f32_e32 v210, v2, v2
	v_fmac_f32_e32 v210, v3, v3
	v_fmac_f32_e32 v210, v4, v4
	v_fmac_f32_e32 v210, v5, v5
	v_fmac_f32_e32 v210, v6, v6
	v_fmac_f32_e32 v210, v7, v7
	v_fmac_f32_e32 v210, v8, v8
	v_fmac_f32_e32 v210, v9, v9
	v_fmac_f32_e32 v210, v10, v10
	v_fmac_f32_e32 v210, v11, v11
	v_fmac_f32_e32 v210, v12, v12
	v_fmac_f32_e32 v210, v13, v13
	v_fmac_f32_e32 v210, v14, v14
	v_fmac_f32_e32 v210, v15, v15
	s_waitcnt vmcnt(24)
	v_mul_f32_e32 v212, v16, v16
	v_fmac_f32_e32 v212, v17, v17
	v_fmac_f32_e32 v212, v18, v18
	v_fmac_f32_e32 v212, v19, v19
	v_fmac_f32_e32 v212, v20, v20
	v_fmac_f32_e32 v212, v21, v21
	v_fmac_f32_e32 v212, v22, v22
	v_fmac_f32_e32 v212, v23, v23
	v_fmac_f32_e32 v212, v24, v24
	v_fmac_f32_e32 v212, v25, v25
	v_fmac_f32_e32 v212, v26, v26
	v_fmac_f32_e32 v212, v27, v27
	v_fmac_f32_e32 v212, v28, v28
	v_fmac_f32_e32 v212, v29, v29
	v_fmac_f32_e32 v212, v30, v30
	v_fmac_f32_e32 v212, v31, v31
	s_waitcnt vmcnt(20)
	v_mul_f32_e32 v214, v32, v32
	v_fmac_f32_e32 v214, v33, v33
	v_fmac_f32_e32 v214, v34, v34
	v_fmac_f32_e32 v214, v35, v35
	v_fmac_f32_e32 v214, v36, v36
	v_fmac_f32_e32 v214, v37, v37
	v_fmac_f32_e32 v214, v38, v38
	v_fmac_f32_e32 v214, v39, v39
	v_fmac_f32_e32 v214, v40, v40
	v_fmac_f32_e32 v214, v41, v41
	v_fmac_f32_e32 v214, v42, v42
	v_fmac_f32_e32 v214, v43, v43
	v_fmac_f32_e32 v214, v44, v44
	v_fmac_f32_e32 v214, v45, v45
	v_fmac_f32_e32 v214, v46, v46
	v_fmac_f32_e32 v214, v47, v47
	s_waitcnt vmcnt(16)
	v_mul_f32_e32 v216, v48, v48
	v_fmac_f32_e32 v216, v49, v49
	v_fmac_f32_e32 v216, v50, v50
	v_fmac_f32_e32 v216, v51, v51
	v_fmac_f32_e32 v216, v52, v52
	v_fmac_f32_e32 v216, v53, v53
	v_fmac_f32_e32 v216, v54, v54
	v_fmac_f32_e32 v216, v55, v55
	v_fmac_f32_e32 v216, v56, v56
	v_fmac_f32_e32 v216, v57, v57
	v_fmac_f32_e32 v216, v58, v58
	v_fmac_f32_e32 v216, v59, v59
	v_fmac_f32_e32 v216, v60, v60
	v_fmac_f32_e32 v216, v61, v61
	v_fmac_f32_e32 v216, v62, v62
	v_fmac_f32_e32 v216, v63, v63
	s_waitcnt vmcnt(12)
	v_mul_f32_e32 v218, v64, v64
	v_fmac_f32_e32 v218, v65, v65
	v_fmac_f32_e32 v218, v66, v66
	v_fmac_f32_e32 v218, v67, v67
	v_fmac_f32_e32 v218, v68, v68
	v_fmac_f32_e32 v218, v69, v69
	v_fmac_f32_e32 v218, v70, v70
	v_fmac_f32_e32 v218, v71, v71
	v_fmac_f32_e32 v218, v72, v72
	v_fmac_f32_e32 v218, v73, v73
	v_fmac_f32_e32 v218, v74, v74
	v_fmac_f32_e32 v218, v75, v75
	v_fmac_f32_e32 v218, v76, v76
	v_fmac_f32_e32 v218, v77, v77
	v_fmac_f32_e32 v218, v78, v78
	v_fmac_f32_e32 v218, v79, v79
	s_waitcnt vmcnt(8)
	v_mul_f32_e32 v220, v80, v80
	v_fmac_f32_e32 v220, v81, v81
	v_fmac_f32_e32 v220, v82, v82
	v_fmac_f32_e32 v220, v83, v83
	v_fmac_f32_e32 v220, v84, v84
	v_fmac_f32_e32 v220, v85, v85
	v_fmac_f32_e32 v220, v86, v86
	v_fmac_f32_e32 v220, v87, v87
	v_fmac_f32_e32 v220, v88, v88
	v_fmac_f32_e32 v220, v89, v89
	v_fmac_f32_e32 v220, v90, v90
	v_fmac_f32_e32 v220, v91, v91
	v_fmac_f32_e32 v220, v92, v92
	v_fmac_f32_e32 v220, v93, v93
	v_fmac_f32_e32 v220, v94, v94
	v_fmac_f32_e32 v220, v95, v95
	s_waitcnt vmcnt(4)
	v_mul_f32_e32 v222, v134, v134
	v_fmac_f32_e32 v222, v135, v135
	v_fmac_f32_e32 v222, v136, v136
	v_fmac_f32_e32 v222, v137, v137
	v_fmac_f32_e32 v222, v138, v138
	v_fmac_f32_e32 v222, v139, v139
	v_fmac_f32_e32 v222, v140, v140
	v_fmac_f32_e32 v222, v141, v141
	v_fmac_f32_e32 v222, v142, v142
	v_fmac_f32_e32 v222, v143, v143
	v_fmac_f32_e32 v222, v144, v144
	v_fmac_f32_e32 v222, v145, v145
	v_fmac_f32_e32 v222, v146, v146
	v_fmac_f32_e32 v222, v147, v147
	v_fmac_f32_e32 v222, v148, v148
	v_fmac_f32_e32 v222, v149, v149
	s_waitcnt vmcnt(0)
	v_mul_f32_e32 v224, v150, v150
	v_fmac_f32_e32 v224, v151, v151
	v_fmac_f32_e32 v224, v152, v152
	v_fmac_f32_e32 v224, v153, v153
	v_fmac_f32_e32 v224, v154, v154
	v_fmac_f32_e32 v224, v155, v155
	v_fmac_f32_e32 v224, v156, v156
	v_fmac_f32_e32 v224, v157, v157
	v_fmac_f32_e32 v224, v158, v158
	v_fmac_f32_e32 v224, v159, v159
	v_fmac_f32_e32 v224, v160, v160
	v_fmac_f32_e32 v224, v161, v161
	v_fmac_f32_e32 v224, v162, v162
	v_fmac_f32_e32 v224, v163, v163
	v_fmac_f32_e32 v224, v164, v164
	v_fmac_f32_e32 v224, v165, v165
	ds_bpermute_b32 v211, v171, v210
	ds_bpermute_b32 v213, v171, v212
	ds_bpermute_b32 v215, v171, v214
	ds_bpermute_b32 v217, v171, v216
	ds_bpermute_b32 v219, v171, v218
	ds_bpermute_b32 v221, v171, v220
	ds_bpermute_b32 v223, v171, v222
	ds_bpermute_b32 v225, v171, v224
	s_waitcnt lgkmcnt(7)
	v_add_f32_e32 v210, v210, v211
	s_waitcnt lgkmcnt(6)
	v_add_f32_e32 v212, v212, v213
	s_waitcnt lgkmcnt(5)
	v_add_f32_e32 v214, v214, v215
	s_waitcnt lgkmcnt(4)
	v_add_f32_e32 v216, v216, v217
	s_waitcnt lgkmcnt(3)
	v_add_f32_e32 v218, v218, v219
	s_waitcnt lgkmcnt(2)
	v_add_f32_e32 v220, v220, v221
	s_waitcnt lgkmcnt(1)
	v_add_f32_e32 v222, v222, v223
	s_waitcnt lgkmcnt(0)
	v_add_f32_e32 v224, v224, v225
	ds_bpermute_b32 v211, v172, v210
	ds_bpermute_b32 v213, v172, v212
	ds_bpermute_b32 v215, v172, v214
	ds_bpermute_b32 v217, v172, v216
	ds_bpermute_b32 v219, v172, v218
	ds_bpermute_b32 v221, v172, v220
	ds_bpermute_b32 v223, v172, v222
	ds_bpermute_b32 v225, v172, v224
	s_waitcnt lgkmcnt(7)
	v_add_f32_e32 v210, v210, v211
	s_waitcnt lgkmcnt(6)
	v_add_f32_e32 v212, v212, v213
	s_waitcnt lgkmcnt(5)
	v_add_f32_e32 v214, v214, v215
	s_waitcnt lgkmcnt(4)
	v_add_f32_e32 v216, v216, v217
	s_waitcnt lgkmcnt(3)
	v_add_f32_e32 v218, v218, v219
	s_waitcnt lgkmcnt(2)
	v_add_f32_e32 v220, v220, v221
	s_waitcnt lgkmcnt(1)
	v_add_f32_e32 v222, v222, v223
	s_waitcnt lgkmcnt(0)
	v_add_f32_e32 v224, v224, v225
	ds_bpermute_b32 v211, v173, v210
	ds_bpermute_b32 v213, v173, v212
	ds_bpermute_b32 v215, v173, v214
	ds_bpermute_b32 v217, v173, v216
	ds_bpermute_b32 v219, v173, v218
	ds_bpermute_b32 v221, v173, v220
	ds_bpermute_b32 v223, v173, v222
	ds_bpermute_b32 v225, v173, v224
	s_waitcnt lgkmcnt(7)
	v_add_f32_e32 v210, v210, v211
	s_waitcnt lgkmcnt(6)
	v_add_f32_e32 v212, v212, v213
	s_waitcnt lgkmcnt(5)
	v_add_f32_e32 v214, v214, v215
	s_waitcnt lgkmcnt(4)
	v_add_f32_e32 v216, v216, v217
	s_waitcnt lgkmcnt(3)
	v_add_f32_e32 v218, v218, v219
	s_waitcnt lgkmcnt(2)
	v_add_f32_e32 v220, v220, v221
	s_waitcnt lgkmcnt(1)
	v_add_f32_e32 v222, v222, v223
	s_waitcnt lgkmcnt(0)
	v_add_f32_e32 v224, v224, v225
	ds_bpermute_b32 v211, v174, v210
	ds_bpermute_b32 v213, v174, v212
	ds_bpermute_b32 v215, v174, v214
	ds_bpermute_b32 v217, v174, v216
	ds_bpermute_b32 v219, v174, v218
	ds_bpermute_b32 v221, v174, v220
	ds_bpermute_b32 v223, v174, v222
	ds_bpermute_b32 v225, v174, v224
	s_waitcnt lgkmcnt(7)
	v_add_f32_e32 v210, v210, v211
	s_waitcnt lgkmcnt(6)
	v_add_f32_e32 v212, v212, v213
	s_waitcnt lgkmcnt(5)
	v_add_f32_e32 v214, v214, v215
	s_waitcnt lgkmcnt(4)
	v_add_f32_e32 v216, v216, v217
	s_waitcnt lgkmcnt(3)
	v_add_f32_e32 v218, v218, v219
	s_waitcnt lgkmcnt(2)
	v_add_f32_e32 v220, v220, v221
	s_waitcnt lgkmcnt(1)
	v_add_f32_e32 v222, v222, v223
	s_waitcnt lgkmcnt(0)
	v_add_f32_e32 v224, v224, v225
	ds_bpermute_b32 v211, v175, v210
	ds_bpermute_b32 v213, v175, v212
	ds_bpermute_b32 v215, v175, v214
	ds_bpermute_b32 v217, v175, v216
	ds_bpermute_b32 v219, v175, v218
	ds_bpermute_b32 v221, v175, v220
	ds_bpermute_b32 v223, v175, v222
	ds_bpermute_b32 v225, v175, v224
	s_waitcnt lgkmcnt(7)
	v_add_f32_e32 v210, v210, v211
	s_waitcnt lgkmcnt(6)
	v_add_f32_e32 v212, v212, v213
	s_waitcnt lgkmcnt(5)
	v_add_f32_e32 v214, v214, v215
	s_waitcnt lgkmcnt(4)
	v_add_f32_e32 v216, v216, v217
	s_waitcnt lgkmcnt(3)
	v_add_f32_e32 v218, v218, v219
	s_waitcnt lgkmcnt(2)
	v_add_f32_e32 v220, v220, v221
	s_waitcnt lgkmcnt(1)
	v_add_f32_e32 v222, v222, v223
	s_waitcnt lgkmcnt(0)
	v_add_f32_e32 v224, v224, v225
	ds_bpermute_b32 v211, v176, v210
	ds_bpermute_b32 v213, v176, v212
	ds_bpermute_b32 v215, v176, v214
	ds_bpermute_b32 v217, v176, v216
	ds_bpermute_b32 v219, v176, v218
	ds_bpermute_b32 v221, v176, v220
	ds_bpermute_b32 v223, v176, v222
	ds_bpermute_b32 v225, v176, v224
	s_waitcnt lgkmcnt(7)
	v_add_f32_e32 v210, v210, v211
	s_waitcnt lgkmcnt(6)
	v_add_f32_e32 v212, v212, v213
	s_waitcnt lgkmcnt(5)
	v_add_f32_e32 v214, v214, v215
	s_waitcnt lgkmcnt(4)
	v_add_f32_e32 v216, v216, v217
	s_waitcnt lgkmcnt(3)
	v_add_f32_e32 v218, v218, v219
	s_waitcnt lgkmcnt(2)
	v_add_f32_e32 v220, v220, v221
	s_waitcnt lgkmcnt(1)
	v_add_f32_e32 v222, v222, v223
	s_waitcnt lgkmcnt(0)
	v_add_f32_e32 v224, v224, v225
	v_fmamk_f32 v210, v210, 0x3a800000, v228
	v_fmamk_f32 v212, v212, 0x3a800000, v228
	v_fmamk_f32 v214, v214, 0x3a800000, v228
	v_fmamk_f32 v216, v216, 0x3a800000, v228
	v_fmamk_f32 v218, v218, 0x3a800000, v228
	v_fmamk_f32 v220, v220, 0x3a800000, v228
	v_fmamk_f32 v222, v222, 0x3a800000, v228
	v_fmamk_f32 v224, v224, 0x3a800000, v228
	v_rsq_f32_e32 v210, v210
	v_rsq_f32_e32 v212, v212
	v_rsq_f32_e32 v214, v214
	v_rsq_f32_e32 v216, v216
	v_rsq_f32_e32 v218, v218
	v_rsq_f32_e32 v220, v220
	v_rsq_f32_e32 v222, v222
	v_rsq_f32_e32 v224, v224
	v_pk_mul_f32 v[0:1], v[0:1], v[210:211] op_sel_hi:[1,0]
	v_pk_mul_f32 v[2:3], v[2:3], v[210:211] op_sel_hi:[1,0]
	v_pk_fma_f32 v[0:1], v[0:1], v[178:179], v[194:195]
	v_pk_fma_f32 v[2:3], v[2:3], v[180:181], v[196:197]
	v_cvt_pk_bf16_f32 v0, v0, v1
	v_cvt_pk_bf16_f32 v1, v2, v3
	global_store_dwordx2 v227, v[0:1], s[56:57]
	v_pk_mul_f32 v[4:5], v[4:5], v[210:211] op_sel_hi:[1,0]
	v_pk_mul_f32 v[6:7], v[6:7], v[210:211] op_sel_hi:[1,0]
	v_pk_fma_f32 v[4:5], v[4:5], v[182:183], v[198:199]
	v_pk_fma_f32 v[6:7], v[6:7], v[184:185], v[200:201]
	v_cvt_pk_bf16_f32 v4, v4, v5
	v_cvt_pk_bf16_f32 v5, v6, v7
	global_store_dwordx2 v227, v[4:5], s[56:57] offset:512
	v_pk_mul_f32 v[8:9], v[8:9], v[210:211] op_sel_hi:[1,0]
	v_pk_mul_f32 v[10:11], v[10:11], v[210:211] op_sel_hi:[1,0]
	v_pk_fma_f32 v[8:9], v[8:9], v[186:187], v[202:203]
	v_pk_fma_f32 v[10:11], v[10:11], v[188:189], v[204:205]
	v_cvt_pk_bf16_f32 v8, v8, v9
	v_cvt_pk_bf16_f32 v9, v10, v11
	global_store_dwordx2 v227, v[8:9], s[56:57] offset:1024
	v_pk_mul_f32 v[12:13], v[12:13], v[210:211] op_sel_hi:[1,0]
	v_pk_mul_f32 v[14:15], v[14:15], v[210:211] op_sel_hi:[1,0]
	v_pk_fma_f32 v[12:13], v[12:13], v[190:191], v[206:207]
	v_pk_fma_f32 v[14:15], v[14:15], v[192:193], v[208:209]
	v_cvt_pk_bf16_f32 v12, v12, v13
	v_cvt_pk_bf16_f32 v13, v14, v15
	global_store_dwordx2 v227, v[12:13], s[56:57] offset:1536
	s_add_u32 s56, s56, 0x4000
	s_addc_u32 s57, s57, 0
	v_pk_mul_f32 v[16:17], v[16:17], v[212:213] op_sel_hi:[1,0]
	v_pk_mul_f32 v[18:19], v[18:19], v[212:213] op_sel_hi:[1,0]
	v_pk_fma_f32 v[16:17], v[16:17], v[178:179], v[194:195]
	v_pk_fma_f32 v[18:19], v[18:19], v[180:181], v[196:197]
	v_cvt_pk_bf16_f32 v16, v16, v17
	v_cvt_pk_bf16_f32 v17, v18, v19
	global_store_dwordx2 v227, v[16:17], s[56:57]
	v_pk_mul_f32 v[20:21], v[20:21], v[212:213] op_sel_hi:[1,0]
	v_pk_mul_f32 v[22:23], v[22:23], v[212:213] op_sel_hi:[1,0]
	v_pk_fma_f32 v[20:21], v[20:21], v[182:183], v[198:199]
	v_pk_fma_f32 v[22:23], v[22:23], v[184:185], v[200:201]
	v_cvt_pk_bf16_f32 v20, v20, v21
	v_cvt_pk_bf16_f32 v21, v22, v23
	global_store_dwordx2 v227, v[20:21], s[56:57] offset:512
	v_pk_mul_f32 v[24:25], v[24:25], v[212:213] op_sel_hi:[1,0]
	v_pk_mul_f32 v[26:27], v[26:27], v[212:213] op_sel_hi:[1,0]
	v_pk_fma_f32 v[24:25], v[24:25], v[186:187], v[202:203]
	v_pk_fma_f32 v[26:27], v[26:27], v[188:189], v[204:205]
	v_cvt_pk_bf16_f32 v24, v24, v25
	v_cvt_pk_bf16_f32 v25, v26, v27
	global_store_dwordx2 v227, v[24:25], s[56:57] offset:1024
	v_pk_mul_f32 v[28:29], v[28:29], v[212:213] op_sel_hi:[1,0]
	v_pk_mul_f32 v[30:31], v[30:31], v[212:213] op_sel_hi:[1,0]
	v_pk_fma_f32 v[28:29], v[28:29], v[190:191], v[206:207]
	v_pk_fma_f32 v[30:31], v[30:31], v[192:193], v[208:209]
	v_cvt_pk_bf16_f32 v28, v28, v29
	v_cvt_pk_bf16_f32 v29, v30, v31
	global_store_dwordx2 v227, v[28:29], s[56:57] offset:1536
	s_add_u32 s56, s56, 0x4000
	s_addc_u32 s57, s57, 0
	v_pk_mul_f32 v[32:33], v[32:33], v[214:215] op_sel_hi:[1,0]
	v_pk_mul_f32 v[34:35], v[34:35], v[214:215] op_sel_hi:[1,0]
	v_pk_fma_f32 v[32:33], v[32:33], v[178:179], v[194:195]
	v_pk_fma_f32 v[34:35], v[34:35], v[180:181], v[196:197]
	v_cvt_pk_bf16_f32 v32, v32, v33
	v_cvt_pk_bf16_f32 v33, v34, v35
	global_store_dwordx2 v227, v[32:33], s[56:57]
	v_pk_mul_f32 v[36:37], v[36:37], v[214:215] op_sel_hi:[1,0]
	v_pk_mul_f32 v[38:39], v[38:39], v[214:215] op_sel_hi:[1,0]
	v_pk_fma_f32 v[36:37], v[36:37], v[182:183], v[198:199]
	v_pk_fma_f32 v[38:39], v[38:39], v[184:185], v[200:201]
	v_cvt_pk_bf16_f32 v36, v36, v37
	v_cvt_pk_bf16_f32 v37, v38, v39
	global_store_dwordx2 v227, v[36:37], s[56:57] offset:512
	v_pk_mul_f32 v[40:41], v[40:41], v[214:215] op_sel_hi:[1,0]
	v_pk_mul_f32 v[42:43], v[42:43], v[214:215] op_sel_hi:[1,0]
	v_pk_fma_f32 v[40:41], v[40:41], v[186:187], v[202:203]
	v_pk_fma_f32 v[42:43], v[42:43], v[188:189], v[204:205]
	v_cvt_pk_bf16_f32 v40, v40, v41
	v_cvt_pk_bf16_f32 v41, v42, v43
	global_store_dwordx2 v227, v[40:41], s[56:57] offset:1024
	v_pk_mul_f32 v[44:45], v[44:45], v[214:215] op_sel_hi:[1,0]
	v_pk_mul_f32 v[46:47], v[46:47], v[214:215] op_sel_hi:[1,0]
	v_pk_fma_f32 v[44:45], v[44:45], v[190:191], v[206:207]
	v_pk_fma_f32 v[46:47], v[46:47], v[192:193], v[208:209]
	v_cvt_pk_bf16_f32 v44, v44, v45
	v_cvt_pk_bf16_f32 v45, v46, v47
	global_store_dwordx2 v227, v[44:45], s[56:57] offset:1536
	s_add_u32 s56, s56, 0x4000
	s_addc_u32 s57, s57, 0
	v_pk_mul_f32 v[48:49], v[48:49], v[216:217] op_sel_hi:[1,0]
	v_pk_mul_f32 v[50:51], v[50:51], v[216:217] op_sel_hi:[1,0]
	v_pk_fma_f32 v[48:49], v[48:49], v[178:179], v[194:195]
	v_pk_fma_f32 v[50:51], v[50:51], v[180:181], v[196:197]
	v_cvt_pk_bf16_f32 v48, v48, v49
	v_cvt_pk_bf16_f32 v49, v50, v51
	global_store_dwordx2 v227, v[48:49], s[56:57]
	v_pk_mul_f32 v[52:53], v[52:53], v[216:217] op_sel_hi:[1,0]
	v_pk_mul_f32 v[54:55], v[54:55], v[216:217] op_sel_hi:[1,0]
	v_pk_fma_f32 v[52:53], v[52:53], v[182:183], v[198:199]
	v_pk_fma_f32 v[54:55], v[54:55], v[184:185], v[200:201]
	v_cvt_pk_bf16_f32 v52, v52, v53
	v_cvt_pk_bf16_f32 v53, v54, v55
	global_store_dwordx2 v227, v[52:53], s[56:57] offset:512
	v_pk_mul_f32 v[56:57], v[56:57], v[216:217] op_sel_hi:[1,0]
	v_pk_mul_f32 v[58:59], v[58:59], v[216:217] op_sel_hi:[1,0]
	v_pk_fma_f32 v[56:57], v[56:57], v[186:187], v[202:203]
	v_pk_fma_f32 v[58:59], v[58:59], v[188:189], v[204:205]
	v_cvt_pk_bf16_f32 v56, v56, v57
	v_cvt_pk_bf16_f32 v57, v58, v59
	global_store_dwordx2 v227, v[56:57], s[56:57] offset:1024
	v_pk_mul_f32 v[60:61], v[60:61], v[216:217] op_sel_hi:[1,0]
	v_pk_mul_f32 v[62:63], v[62:63], v[216:217] op_sel_hi:[1,0]
	v_pk_fma_f32 v[60:61], v[60:61], v[190:191], v[206:207]
	v_pk_fma_f32 v[62:63], v[62:63], v[192:193], v[208:209]
	v_cvt_pk_bf16_f32 v60, v60, v61
	v_cvt_pk_bf16_f32 v61, v62, v63
	global_store_dwordx2 v227, v[60:61], s[56:57] offset:1536
	s_add_u32 s56, s56, 0x4000
	s_addc_u32 s57, s57, 0
	v_pk_mul_f32 v[64:65], v[64:65], v[218:219] op_sel_hi:[1,0]
	v_pk_mul_f32 v[66:67], v[66:67], v[218:219] op_sel_hi:[1,0]
	v_pk_fma_f32 v[64:65], v[64:65], v[178:179], v[194:195]
	v_pk_fma_f32 v[66:67], v[66:67], v[180:181], v[196:197]
	v_cvt_pk_bf16_f32 v64, v64, v65
	v_cvt_pk_bf16_f32 v65, v66, v67
	global_store_dwordx2 v227, v[64:65], s[56:57]
	v_pk_mul_f32 v[68:69], v[68:69], v[218:219] op_sel_hi:[1,0]
	v_pk_mul_f32 v[70:71], v[70:71], v[218:219] op_sel_hi:[1,0]
	v_pk_fma_f32 v[68:69], v[68:69], v[182:183], v[198:199]
	v_pk_fma_f32 v[70:71], v[70:71], v[184:185], v[200:201]
	v_cvt_pk_bf16_f32 v68, v68, v69
	v_cvt_pk_bf16_f32 v69, v70, v71
	global_store_dwordx2 v227, v[68:69], s[56:57] offset:512
	v_pk_mul_f32 v[72:73], v[72:73], v[218:219] op_sel_hi:[1,0]
	v_pk_mul_f32 v[74:75], v[74:75], v[218:219] op_sel_hi:[1,0]
	v_pk_fma_f32 v[72:73], v[72:73], v[186:187], v[202:203]
	v_pk_fma_f32 v[74:75], v[74:75], v[188:189], v[204:205]
	v_cvt_pk_bf16_f32 v72, v72, v73
	v_cvt_pk_bf16_f32 v73, v74, v75
	global_store_dwordx2 v227, v[72:73], s[56:57] offset:1024
	v_pk_mul_f32 v[76:77], v[76:77], v[218:219] op_sel_hi:[1,0]
	v_pk_mul_f32 v[78:79], v[78:79], v[218:219] op_sel_hi:[1,0]
	v_pk_fma_f32 v[76:77], v[76:77], v[190:191], v[206:207]
	v_pk_fma_f32 v[78:79], v[78:79], v[192:193], v[208:209]
	v_cvt_pk_bf16_f32 v76, v76, v77
	v_cvt_pk_bf16_f32 v77, v78, v79
	global_store_dwordx2 v227, v[76:77], s[56:57] offset:1536
	s_add_u32 s56, s56, 0x4000
	s_addc_u32 s57, s57, 0
	v_pk_mul_f32 v[80:81], v[80:81], v[220:221] op_sel_hi:[1,0]
	v_pk_mul_f32 v[82:83], v[82:83], v[220:221] op_sel_hi:[1,0]
	v_pk_fma_f32 v[80:81], v[80:81], v[178:179], v[194:195]
	v_pk_fma_f32 v[82:83], v[82:83], v[180:181], v[196:197]
	v_cvt_pk_bf16_f32 v80, v80, v81
	v_cvt_pk_bf16_f32 v81, v82, v83
	global_store_dwordx2 v227, v[80:81], s[56:57]
	v_pk_mul_f32 v[84:85], v[84:85], v[220:221] op_sel_hi:[1,0]
	v_pk_mul_f32 v[86:87], v[86:87], v[220:221] op_sel_hi:[1,0]
	v_pk_fma_f32 v[84:85], v[84:85], v[182:183], v[198:199]
	v_pk_fma_f32 v[86:87], v[86:87], v[184:185], v[200:201]
	v_cvt_pk_bf16_f32 v84, v84, v85
	v_cvt_pk_bf16_f32 v85, v86, v87
	global_store_dwordx2 v227, v[84:85], s[56:57] offset:512
	v_pk_mul_f32 v[88:89], v[88:89], v[220:221] op_sel_hi:[1,0]
	v_pk_mul_f32 v[90:91], v[90:91], v[220:221] op_sel_hi:[1,0]
	v_pk_fma_f32 v[88:89], v[88:89], v[186:187], v[202:203]
	v_pk_fma_f32 v[90:91], v[90:91], v[188:189], v[204:205]
	v_cvt_pk_bf16_f32 v88, v88, v89
	v_cvt_pk_bf16_f32 v89, v90, v91
	global_store_dwordx2 v227, v[88:89], s[56:57] offset:1024
	v_pk_mul_f32 v[92:93], v[92:93], v[220:221] op_sel_hi:[1,0]
	v_pk_mul_f32 v[94:95], v[94:95], v[220:221] op_sel_hi:[1,0]
	v_pk_fma_f32 v[92:93], v[92:93], v[190:191], v[206:207]
	v_pk_fma_f32 v[94:95], v[94:95], v[192:193], v[208:209]
	v_cvt_pk_bf16_f32 v92, v92, v93
	v_cvt_pk_bf16_f32 v93, v94, v95
	global_store_dwordx2 v227, v[92:93], s[56:57] offset:1536
	s_add_u32 s56, s56, 0x4000
	s_addc_u32 s57, s57, 0
	v_pk_mul_f32 v[134:135], v[134:135], v[222:223] op_sel_hi:[1,0]
	v_pk_mul_f32 v[136:137], v[136:137], v[222:223] op_sel_hi:[1,0]
	v_pk_fma_f32 v[134:135], v[134:135], v[178:179], v[194:195]
	v_pk_fma_f32 v[136:137], v[136:137], v[180:181], v[196:197]
	v_cvt_pk_bf16_f32 v134, v134, v135
	v_cvt_pk_bf16_f32 v135, v136, v137
	global_store_dwordx2 v227, v[134:135], s[56:57]
	v_pk_mul_f32 v[138:139], v[138:139], v[222:223] op_sel_hi:[1,0]
	v_pk_mul_f32 v[140:141], v[140:141], v[222:223] op_sel_hi:[1,0]
	v_pk_fma_f32 v[138:139], v[138:139], v[182:183], v[198:199]
	v_pk_fma_f32 v[140:141], v[140:141], v[184:185], v[200:201]
	v_cvt_pk_bf16_f32 v138, v138, v139
	v_cvt_pk_bf16_f32 v139, v140, v141
	global_store_dwordx2 v227, v[138:139], s[56:57] offset:512
	v_pk_mul_f32 v[142:143], v[142:143], v[222:223] op_sel_hi:[1,0]
	v_pk_mul_f32 v[144:145], v[144:145], v[222:223] op_sel_hi:[1,0]
	v_pk_fma_f32 v[142:143], v[142:143], v[186:187], v[202:203]
	v_pk_fma_f32 v[144:145], v[144:145], v[188:189], v[204:205]
	v_cvt_pk_bf16_f32 v142, v142, v143
	v_cvt_pk_bf16_f32 v143, v144, v145
	global_store_dwordx2 v227, v[142:143], s[56:57] offset:1024
	v_pk_mul_f32 v[146:147], v[146:147], v[222:223] op_sel_hi:[1,0]
	v_pk_mul_f32 v[148:149], v[148:149], v[222:223] op_sel_hi:[1,0]
	v_pk_fma_f32 v[146:147], v[146:147], v[190:191], v[206:207]
	v_pk_fma_f32 v[148:149], v[148:149], v[192:193], v[208:209]
	v_cvt_pk_bf16_f32 v146, v146, v147
	v_cvt_pk_bf16_f32 v147, v148, v149
	global_store_dwordx2 v227, v[146:147], s[56:57] offset:1536
	s_add_u32 s56, s56, 0x4000
	s_addc_u32 s57, s57, 0
	v_pk_mul_f32 v[150:151], v[150:151], v[224:225] op_sel_hi:[1,0]
	v_pk_mul_f32 v[152:153], v[152:153], v[224:225] op_sel_hi:[1,0]
	v_pk_fma_f32 v[150:151], v[150:151], v[178:179], v[194:195]
	v_pk_fma_f32 v[152:153], v[152:153], v[180:181], v[196:197]
	v_cvt_pk_bf16_f32 v150, v150, v151
	v_cvt_pk_bf16_f32 v151, v152, v153
	global_store_dwordx2 v227, v[150:151], s[56:57]
	v_pk_mul_f32 v[154:155], v[154:155], v[224:225] op_sel_hi:[1,0]
	v_pk_mul_f32 v[156:157], v[156:157], v[224:225] op_sel_hi:[1,0]
	v_pk_fma_f32 v[154:155], v[154:155], v[182:183], v[198:199]
	v_pk_fma_f32 v[156:157], v[156:157], v[184:185], v[200:201]
	v_cvt_pk_bf16_f32 v154, v154, v155
	v_cvt_pk_bf16_f32 v155, v156, v157
	global_store_dwordx2 v227, v[154:155], s[56:57] offset:512
	v_pk_mul_f32 v[158:159], v[158:159], v[224:225] op_sel_hi:[1,0]
	v_pk_mul_f32 v[160:161], v[160:161], v[224:225] op_sel_hi:[1,0]
	v_pk_fma_f32 v[158:159], v[158:159], v[186:187], v[202:203]
	v_pk_fma_f32 v[160:161], v[160:161], v[188:189], v[204:205]
	v_cvt_pk_bf16_f32 v158, v158, v159
	v_cvt_pk_bf16_f32 v159, v160, v161
	global_store_dwordx2 v227, v[158:159], s[56:57] offset:1024
	v_pk_mul_f32 v[162:163], v[162:163], v[224:225] op_sel_hi:[1,0]
	v_pk_mul_f32 v[164:165], v[164:165], v[224:225] op_sel_hi:[1,0]
	v_pk_fma_f32 v[162:163], v[162:163], v[190:191], v[206:207]
	v_pk_fma_f32 v[164:165], v[164:165], v[192:193], v[208:209]
	v_cvt_pk_bf16_f32 v162, v162, v163
	v_cvt_pk_bf16_f32 v163, v164, v165
	global_store_dwordx2 v227, v[162:163], s[56:57] offset:1536

.LBB0_1472:
	global_load_dword v1, v0, s[16:17] sc1
	s_mov_b64 s[18:19], -1
	s_waitcnt vmcnt(0)
	v_cmp_lt_u32_e32 vcc, 3, v1
	s_cbranch_vccnz .LBB0_1471
	s_sleep 2
	global_load_dword v1, v0, s[16:17] sc1
	s_waitcnt vmcnt(0)
	v_cmp_gt_u32_e32 vcc, 4, v1
	s_cbranch_vccz .LBB0_1471
	s_sleep 2
	global_load_dword v1, v0, s[16:17] sc1
	s_waitcnt vmcnt(0)
	v_cmp_gt_u32_e32 vcc, 4, v1
	s_cbranch_vccz .LBB0_1471
	s_sleep 2
	global_load_dword v1, v0, s[16:17] sc1
	s_waitcnt vmcnt(0)
	v_cmp_gt_u32_e32 vcc, 4, v1
	s_cbranch_vccz .LBB0_1471
	s_sleep 2
	global_load_dword v1, v0, s[16:17] sc1
	s_waitcnt vmcnt(0)
	v_cmp_gt_u32_e32 vcc, 4, v1
	s_cbranch_vccz .LBB0_1471
	s_add_i32 s13, s13, -5
	s_cmp_eq_u32 s13, 0
	s_cselect_b64 s[18:19], -1, 0
	s_sleep 2
	s_branch .LBB0_1471
.LBB0_1478:
	s_waitcnt vmcnt(0)
.LBB0_1479:
	s_or_b64 exec, exec, s[14:15]
	s_sext_i32_i8 s13, s30
	s_lshl_b32 s12, s12, 8
	s_lshl_b32 s16, s13, 6
	s_add_i32 s50, s12, s16
	s_add_u32 s40, s22, 0x56bc000
	s_addc_u32 s41, s23, 0
	s_add_i32 s50, s50, 64
	s_add_u32 s26, s22, 0x76bc000
	s_addc_u32 s27, s23, 0
	s_lshl_b32 s18, s29, 8
	s_lshl_b32 s17, s28, 11
	s_add_i32 s16, s16, s18
	v_lshrrev_b32_e32 v1, 6, v170
	s_add_i32 s16, s16, s17
	v_mov_b32_e32 v0, v170
	v_or_b32_e32 v50, s16, v1
	s_waitcnt lgkmcnt(0)
	s_barrier
	s_load_dwordx2 s[52:53], s[0:1], 0xe8
	s_sub_i32 s66, s50, 64
	v_readfirstlane_b32 s60, v170
	v_and_b32_e32 v194, 63, v170
	v_lshrrev_b32_e32 v195, 6, v170
	v_and_b32_e32 v196, 15, v194
	v_lshrrev_b32_e32 v194, 4, v194
	v_and_b32_e32 v197, 3, v195
	v_lshrrev_b32_e32 v195, 2, v195
	v_lshl_add_u32 v196, v195, 6, v196
	v_lshl_add_u32 v197, v197, 5, 0
	v_lshl_add_u32 v197, v194, 2, v197
	s_lshr_b32 s64, s66, 8
	s_lshr_b32 s65, s66, 6
	s_and_b32 s65, s65, 3
	s_lshl_b32 s67, s65, 8
	v_add_u32_e32 v197, s67, v197
	s_waitcnt lgkmcnt(0)
	s_lshl_b32 s61, s64, 12
	s_add_u32 s62, s52, s61
	s_addc_u32 s63, s53, 0
	s_add_u32 s62, s62, 0x40000
	s_addc_u32 s63, s63, 0
	s_cmp_lt_u32 s60, 256
	s_cbranch_scc0 .Lf2p10_nor
	v_lshlrev_b32_e32 v190, 2, v170
	global_load_dword v192, v190, s[62:63] sc1
	global_load_dword v193, v190, s[62:63] offset:1024 sc1
	global_load_dword v198, v190, s[62:63] offset:2048 sc1
	global_load_dword v199, v190, s[62:63] offset:3072 sc1
	v_mov_b32_e32 v191, 0x358637bd
	s_waitcnt vmcnt(0)
	v_add_f32_e32 v192, v192, v193
	v_add_f32_e32 v198, v198, v199
	v_add_f32_e32 v192, v192, v198
	v_fmamk_f32 v192, v192, 0x3a800000, v191
	v_rsq_f32_e32 v192, v192
	v_add_u32_e32 v191, 0x21000, v190
	s_nop 0
	ds_write_b32 v191, v192
	s_cmp_lg_u32 s65, 0
	s_cbranch_scc1 .Lf2p10_nor
	s_lshl_b32 s61, s64, 10
	s_add_u32 s62, s52, 0x76bc000
	s_addc_u32 s63, s53, 0
	s_add_u32 s62, s62, s61
	s_addc_u32 s63, s63, 0
	global_store_dword v190, v192, s[62:63]

.LBB0_1841:
	global_load_dword v1, v0, s[22:23] sc1
	s_mov_b64 s[24:25], -1
	s_waitcnt vmcnt(0)
	v_cmp_lt_u32_e32 vcc, 3, v1
	s_cbranch_vccnz .LBB0_1840
	s_sleep 2
	global_load_dword v1, v0, s[22:23] sc1
	s_waitcnt vmcnt(0)
	v_cmp_gt_u32_e32 vcc, 4, v1
	s_cbranch_vccz .LBB0_1840
	s_sleep 2
	global_load_dword v1, v0, s[22:23] sc1
	s_waitcnt vmcnt(0)
	v_cmp_gt_u32_e32 vcc, 4, v1
	s_cbranch_vccz .LBB0_1840
	s_sleep 2
	global_load_dword v1, v0, s[22:23] sc1
	s_waitcnt vmcnt(0)
	v_cmp_gt_u32_e32 vcc, 4, v1
	s_cbranch_vccz .LBB0_1840
	s_sleep 2
	global_load_dword v1, v0, s[22:23] sc1
	s_waitcnt vmcnt(0)
	v_cmp_gt_u32_e32 vcc, 4, v1
	s_cbranch_vccz .LBB0_1840
	s_add_i32 s13, s13, -5
	s_cmp_eq_u32 s13, 0
	s_cselect_b64 s[24:25], -1, 0
	s_sleep 2
	s_branch .LBB0_1840
.LBB0_1847:
	s_waitcnt vmcnt(0)
.LBB0_1848:
	s_or_b64 exec, exec, s[20:21]
	s_sext_i32_i8 s13, s30
	s_lshl_b32 s12, s12, 8
	s_lshl_b32 s13, s13, 6
	s_add_i32 s36, s12, s13
	v_mov_b32_e32 v1, v170
	s_barrier
	s_load_dwordx2 s[52:53], s[0:1], 0xe8
	s_mov_b32 s66, s36
	v_readfirstlane_b32 s65, v170
	v_and_b32_e32 v226, 63, v170
	v_mov_b32_e32 v228, 0x358637bd
	v_lshlrev_b32_e32 v227, 3, v226
	v_lshlrev_b32_e32 v226, 4, v226
	s_lshr_b32 s65, s65, 6
	s_add_i32 s66, s66, s65
	s_waitcnt lgkmcnt(0)
	s_sub_i32 s67, s66, 0x1000
	s_ashr_i32 s67, s67, 11
	s_add_i32 s67, s67, 1
	s_cmp_gt_i32 s66, 0xfff
	s_cselect_b32 s67, s67, 0
	s_add_i32 s67, s67, 5
	s_mul_i32 s67, s67, 6
	s_add_i32 s67, s67, 3
	s_lshl_b32 s67, s67, 12
	s_add_u32 s58, s52, 0x780000
	s_addc_u32 s59, s53, 0
	s_add_u32 s58, s58, s67
	s_addc_u32 s59, s59, 0
	s_add_u32 s60, s58, 0x1000
	s_addc_u32 s61, s59, 0
	global_load_dwordx4 v[178:181], v226, s[58:59]
	global_load_dwordx4 v[182:185], v226, s[58:59] offset:1024
	global_load_dwordx4 v[186:189], v226, s[58:59] offset:2048
	global_load_dwordx4 v[190:193], v226, s[58:59] offset:3072
	global_load_dwordx4 v[194:197], v226, s[60:61]
	global_load_dwordx4 v[198:201], v226, s[60:61] offset:1024
	global_load_dwordx4 v[202:205], v226, s[60:61] offset:2048
	global_load_dwordx4 v[206:209], v226, s[60:61] offset:3072
	s_lshl_b32 s67, s66, 11
	s_add_u32 s56, s52, 0x2ebc000
	s_addc_u32 s57, s53, 0
	s_add_u32 s56, s56, s67
	s_addc_u32 s57, s57, 0
	s_lshl_b32 s67, s66, 12
	s_add_u32 s54, s52, 0x46bc000
	s_addc_u32 s55, s53, 0
	s_add_u32 s54, s54, s67
	s_addc_u32 s55, s55, 0
	global_load_dwordx4 v[0:3], v226, s[54:55] sc1
	global_load_dwordx4 v[4:7], v226, s[54:55] offset:1024 sc1
	global_load_dwordx4 v[8:11], v226, s[54:55] offset:2048 sc1
	global_load_dwordx4 v[12:15], v226, s[54:55] offset:3072 sc1
	s_add_u32 s54, s54, 0x8000
	s_addc_u32 s55, s55, 0
	global_load_dwordx4 v[16:19], v226, s[54:55] sc1
	global_load_dwordx4 v[20:23], v226, s[54:55] offset:1024 sc1
	global_load_dwordx4 v[24:27], v226, s[54:55] offset:2048 sc1
	global_load_dwordx4 v[28:31], v226, s[54:55] offset:3072 sc1
	s_add_u32 s54, s54, 0x8000
	s_addc_u32 s55, s55, 0
	global_load_dwordx4 v[32:35], v226, s[54:55] sc1
	global_load_dwordx4 v[36:39], v226, s[54:55] offset:1024 sc1
	global_load_dwordx4 v[40:43], v226, s[54:55] offset:2048 sc1
	global_load_dwordx4 v[44:47], v226, s[54:55] offset:3072 sc1
	s_add_u32 s54, s54, 0x8000
	s_addc_u32 s55, s55, 0
	global_load_dwordx4 v[48:51], v226, s[54:55] sc1
	global_load_dwordx4 v[52:55], v226, s[54:55] offset:1024 sc1
	global_load_dwordx4 v[56:59], v226, s[54:55] offset:2048 sc1
	global_load_dwordx4 v[60:63], v226, s[54:55] offset:3072 sc1
	s_add_u32 s54, s54, 0x8000
	s_addc_u32 s55, s55, 0
	global_load_dwordx4 v[64:67], v226, s[54:55] sc1
	global_load_dwordx4 v[68:71], v226, s[54:55] offset:1024 sc1
	global_load_dwordx4 v[72:75], v226, s[54:55] offset:2048 sc1
	global_load_dwordx4 v[76:79], v226, s[54:55] offset:3072 sc1
	s_add_u32 s54, s54, 0x8000
	s_addc_u32 s55, s55, 0
	global_load_dwordx4 v[80:83], v226, s[54:55] sc1
	global_load_dwordx4 v[84:87], v226, s[54:55] offset:1024 sc1
	global_load_dwordx4 v[88:91], v226, s[54:55] offset:2048 sc1
	global_load_dwordx4 v[92:95], v226, s[54:55] offset:3072 sc1
	s_add_u32 s54, s54, 0x8000
	s_addc_u32 s55, s55, 0
	global_load_dwordx4 v[134:137], v226, s[54:55] sc1
	global_load_dwordx4 v[138:141], v226, s[54:55] offset:1024 sc1
	global_load_dwordx4 v[142:145], v226, s[54:55] offset:2048 sc1
	global_load_dwordx4 v[146:149], v226, s[54:55] offset:3072 sc1
	s_add_u32 s54, s54, 0x8000
	s_addc_u32 s55, s55, 0
	global_load_dwordx4 v[150:153], v226, s[54:55] sc1
	global_load_dwordx4 v[154:157], v226, s[54:55] offset:1024 sc1
	global_load_dwordx4 v[158:161], v226, s[54:55] offset:2048 sc1
	global_load_dwordx4 v[162:165], v226, s[54:55] offset:3072 sc1
	s_waitcnt vmcnt(28)
	v_mul_f32_e32 v210, v0, v0
	v_fmac_f32_e32 v210, v1, v1
	v_fmac_f32_e32 v210, v2, v2
	v_fmac_f32_e32 v210, v3, v3
	v_fmac_f32_e32 v210, v4, v4
	v_fmac_f32_e32 v210, v5, v5
	v_fmac_f32_e32 v210, v6, v6
	v_fmac_f32_e32 v210, v7, v7
	v_fmac_f32_e32 v210, v8, v8
	v_fmac_f32_e32 v210, v9, v9
	v_fmac_f32_e32 v210, v10, v10
	v_fmac_f32_e32 v210, v11, v11
	v_fmac_f32_e32 v210, v12, v12
	v_fmac_f32_e32 v210, v13, v13
	v_fmac_f32_e32 v210, v14, v14
	v_fmac_f32_e32 v210, v15, v15
	s_waitcnt vmcnt(24)
	v_mul_f32_e32 v212, v16, v16
	v_fmac_f32_e32 v212, v17, v17
	v_fmac_f32_e32 v212, v18, v18
	v_fmac_f32_e32 v212, v19, v19
	v_fmac_f32_e32 v212, v20, v20
	v_fmac_f32_e32 v212, v21, v21
	v_fmac_f32_e32 v212, v22, v22
	v_fmac_f32_e32 v212, v23, v23
	v_fmac_f32_e32 v212, v24, v24
	v_fmac_f32_e32 v212, v25, v25
	v_fmac_f32_e32 v212, v26, v26
	v_fmac_f32_e32 v212, v27, v27
	v_fmac_f32_e32 v212, v28, v28
	v_fmac_f32_e32 v212, v29, v29
	v_fmac_f32_e32 v212, v30, v30
	v_fmac_f32_e32 v212, v31, v31
	s_waitcnt vmcnt(20)
	v_mul_f32_e32 v214, v32, v32
	v_fmac_f32_e32 v214, v33, v33
	v_fmac_f32_e32 v214, v34, v34
	v_fmac_f32_e32 v214, v35, v35
	v_fmac_f32_e32 v214, v36, v36
	v_fmac_f32_e32 v214, v37, v37
	v_fmac_f32_e32 v214, v38, v38
	v_fmac_f32_e32 v214, v39, v39
	v_fmac_f32_e32 v214, v40, v40
	v_fmac_f32_e32 v214, v41, v41
	v_fmac_f32_e32 v214, v42, v42
	v_fmac_f32_e32 v214, v43, v43
	v_fmac_f32_e32 v214, v44, v44
	v_fmac_f32_e32 v214, v45, v45
	v_fmac_f32_e32 v214, v46, v46
	v_fmac_f32_e32 v214, v47, v47
	s_waitcnt vmcnt(16)
	v_mul_f32_e32 v216, v48, v48
	v_fmac_f32_e32 v216, v49, v49
	v_fmac_f32_e32 v216, v50, v50
	v_fmac_f32_e32 v216, v51, v51
	v_fmac_f32_e32 v216, v52, v52
	v_fmac_f32_e32 v216, v53, v53
	v_fmac_f32_e32 v216, v54, v54
	v_fmac_f32_e32 v216, v55, v55
	v_fmac_f32_e32 v216, v56, v56
	v_fmac_f32_e32 v216, v57, v57
	v_fmac_f32_e32 v216, v58, v58
	v_fmac_f32_e32 v216, v59, v59
	v_fmac_f32_e32 v216, v60, v60
	v_fmac_f32_e32 v216, v61, v61
	v_fmac_f32_e32 v216, v62, v62
	v_fmac_f32_e32 v216, v63, v63
	s_waitcnt vmcnt(12)
	v_mul_f32_e32 v218, v64, v64
	v_fmac_f32_e32 v218, v65, v65
	v_fmac_f32_e32 v218, v66, v66
	v_fmac_f32_e32 v218, v67, v67
	v_fmac_f32_e32 v218, v68, v68
	v_fmac_f32_e32 v218, v69, v69
	v_fmac_f32_e32 v218, v70, v70
	v_fmac_f32_e32 v218, v71, v71
	v_fmac_f32_e32 v218, v72, v72
	v_fmac_f32_e32 v218, v73, v73
	v_fmac_f32_e32 v218, v74, v74
	v_fmac_f32_e32 v218, v75, v75
	v_fmac_f32_e32 v218, v76, v76
	v_fmac_f32_e32 v218, v77, v77
	v_fmac_f32_e32 v218, v78, v78
	v_fmac_f32_e32 v218, v79, v79
	s_waitcnt vmcnt(8)
	v_mul_f32_e32 v220, v80, v80
	v_fmac_f32_e32 v220, v81, v81
	v_fmac_f32_e32 v220, v82, v82
	v_fmac_f32_e32 v220, v83, v83
	v_fmac_f32_e32 v220, v84, v84
	v_fmac_f32_e32 v220, v85, v85
	v_fmac_f32_e32 v220, v86, v86
	v_fmac_f32_e32 v220, v87, v87
	v_fmac_f32_e32 v220, v88, v88
	v_fmac_f32_e32 v220, v89, v89
	v_fmac_f32_e32 v220, v90, v90
	v_fmac_f32_e32 v220, v91, v91
	v_fmac_f32_e32 v220, v92, v92
	v_fmac_f32_e32 v220, v93, v93
	v_fmac_f32_e32 v220, v94, v94
	v_fmac_f32_e32 v220, v95, v95
	s_waitcnt vmcnt(4)
	v_mul_f32_e32 v222, v134, v134
	v_fmac_f32_e32 v222, v135, v135
	v_fmac_f32_e32 v222, v136, v136
	v_fmac_f32_e32 v222, v137, v137
	v_fmac_f32_e32 v222, v138, v138
	v_fmac_f32_e32 v222, v139, v139
	v_fmac_f32_e32 v222, v140, v140
	v_fmac_f32_e32 v222, v141, v141
	v_fmac_f32_e32 v222, v142, v142
	v_fmac_f32_e32 v222, v143, v143
	v_fmac_f32_e32 v222, v144, v144
	v_fmac_f32_e32 v222, v145, v145
	v_fmac_f32_e32 v222, v146, v146
	v_fmac_f32_e32 v222, v147, v147
	v_fmac_f32_e32 v222, v148, v148
	v_fmac_f32_e32 v222, v149, v149
	s_waitcnt vmcnt(0)
	v_mul_f32_e32 v224, v150, v150
	v_fmac_f32_e32 v224, v151, v151
	v_fmac_f32_e32 v224, v152, v152
	v_fmac_f32_e32 v224, v153, v153
	v_fmac_f32_e32 v224, v154, v154
	v_fmac_f32_e32 v224, v155, v155
	v_fmac_f32_e32 v224, v156, v156
	v_fmac_f32_e32 v224, v157, v157
	v_fmac_f32_e32 v224, v158, v158
	v_fmac_f32_e32 v224, v159, v159
	v_fmac_f32_e32 v224, v160, v160
	v_fmac_f32_e32 v224, v161, v161
	v_fmac_f32_e32 v224, v162, v162
	v_fmac_f32_e32 v224, v163, v163
	v_fmac_f32_e32 v224, v164, v164
	v_fmac_f32_e32 v224, v165, v165
	ds_bpermute_b32 v211, v171, v210
	ds_bpermute_b32 v213, v171, v212
	ds_bpermute_b32 v215, v171, v214
	ds_bpermute_b32 v217, v171, v216
	ds_bpermute_b32 v219, v171, v218
	ds_bpermute_b32 v221, v171, v220
	ds_bpermute_b32 v223, v171, v222
	ds_bpermute_b32 v225, v171, v224
	s_waitcnt lgkmcnt(7)
	v_add_f32_e32 v210, v210, v211
	s_waitcnt lgkmcnt(6)
	v_add_f32_e32 v212, v212, v213
	s_waitcnt lgkmcnt(5)
	v_add_f32_e32 v214, v214, v215
	s_waitcnt lgkmcnt(4)
	v_add_f32_e32 v216, v216, v217
	s_waitcnt lgkmcnt(3)
	v_add_f32_e32 v218, v218, v219
	s_waitcnt lgkmcnt(2)
	v_add_f32_e32 v220, v220, v221
	s_waitcnt lgkmcnt(1)
	v_add_f32_e32 v222, v222, v223
	s_waitcnt lgkmcnt(0)
	v_add_f32_e32 v224, v224, v225
	ds_bpermute_b32 v211, v172, v210
	ds_bpermute_b32 v213, v172, v212
	ds_bpermute_b32 v215, v172, v214
	ds_bpermute_b32 v217, v172, v216
	ds_bpermute_b32 v219, v172, v218
	ds_bpermute_b32 v221, v172, v220
	ds_bpermute_b32 v223, v172, v222
	ds_bpermute_b32 v225, v172, v224
	s_waitcnt lgkmcnt(7)
	v_add_f32_e32 v210, v210, v211
	s_waitcnt lgkmcnt(6)
	v_add_f32_e32 v212, v212, v213
	s_waitcnt lgkmcnt(5)
	v_add_f32_e32 v214, v214, v215
	s_waitcnt lgkmcnt(4)
	v_add_f32_e32 v216, v216, v217
	s_waitcnt lgkmcnt(3)
	v_add_f32_e32 v218, v218, v219
	s_waitcnt lgkmcnt(2)
	v_add_f32_e32 v220, v220, v221
	s_waitcnt lgkmcnt(1)
	v_add_f32_e32 v222, v222, v223
	s_waitcnt lgkmcnt(0)
	v_add_f32_e32 v224, v224, v225
	ds_bpermute_b32 v211, v173, v210
	ds_bpermute_b32 v213, v173, v212
	ds_bpermute_b32 v215, v173, v214
	ds_bpermute_b32 v217, v173, v216
	ds_bpermute_b32 v219, v173, v218
	ds_bpermute_b32 v221, v173, v220
	ds_bpermute_b32 v223, v173, v222
	ds_bpermute_b32 v225, v173, v224
	s_waitcnt lgkmcnt(7)
	v_add_f32_e32 v210, v210, v211
	s_waitcnt lgkmcnt(6)
	v_add_f32_e32 v212, v212, v213
	s_waitcnt lgkmcnt(5)
	v_add_f32_e32 v214, v214, v215
	s_waitcnt lgkmcnt(4)
	v_add_f32_e32 v216, v216, v217
	s_waitcnt lgkmcnt(3)
	v_add_f32_e32 v218, v218, v219
	s_waitcnt lgkmcnt(2)
	v_add_f32_e32 v220, v220, v221
	s_waitcnt lgkmcnt(1)
	v_add_f32_e32 v222, v222, v223
	s_waitcnt lgkmcnt(0)
	v_add_f32_e32 v224, v224, v225
	ds_bpermute_b32 v211, v174, v210
	ds_bpermute_b32 v213, v174, v212
	ds_bpermute_b32 v215, v174, v214
	ds_bpermute_b32 v217, v174, v216
	ds_bpermute_b32 v219, v174, v218
	ds_bpermute_b32 v221, v174, v220
	ds_bpermute_b32 v223, v174, v222
	ds_bpermute_b32 v225, v174, v224
	s_waitcnt lgkmcnt(7)
	v_add_f32_e32 v210, v210, v211
	s_waitcnt lgkmcnt(6)
	v_add_f32_e32 v212, v212, v213
	s_waitcnt lgkmcnt(5)
	v_add_f32_e32 v214, v214, v215
	s_waitcnt lgkmcnt(4)
	v_add_f32_e32 v216, v216, v217
	s_waitcnt lgkmcnt(3)
	v_add_f32_e32 v218, v218, v219
	s_waitcnt lgkmcnt(2)
	v_add_f32_e32 v220, v220, v221
	s_waitcnt lgkmcnt(1)
	v_add_f32_e32 v222, v222, v223
	s_waitcnt lgkmcnt(0)
	v_add_f32_e32 v224, v224, v225
	ds_bpermute_b32 v211, v175, v210
	ds_bpermute_b32 v213, v175, v212
	ds_bpermute_b32 v215, v175, v214
	ds_bpermute_b32 v217, v175, v216
	ds_bpermute_b32 v219, v175, v218
	ds_bpermute_b32 v221, v175, v220
	ds_bpermute_b32 v223, v175, v222
	ds_bpermute_b32 v225, v175, v224
	s_waitcnt lgkmcnt(7)
	v_add_f32_e32 v210, v210, v211
	s_waitcnt lgkmcnt(6)
	v_add_f32_e32 v212, v212, v213
	s_waitcnt lgkmcnt(5)
	v_add_f32_e32 v214, v214, v215
	s_waitcnt lgkmcnt(4)
	v_add_f32_e32 v216, v216, v217
	s_waitcnt lgkmcnt(3)
	v_add_f32_e32 v218, v218, v219
	s_waitcnt lgkmcnt(2)
	v_add_f32_e32 v220, v220, v221
	s_waitcnt lgkmcnt(1)
	v_add_f32_e32 v222, v222, v223
	s_waitcnt lgkmcnt(0)
	v_add_f32_e32 v224, v224, v225
	ds_bpermute_b32 v211, v176, v210
	ds_bpermute_b32 v213, v176, v212
	ds_bpermute_b32 v215, v176, v214
	ds_bpermute_b32 v217, v176, v216
	ds_bpermute_b32 v219, v176, v218
	ds_bpermute_b32 v221, v176, v220
	ds_bpermute_b32 v223, v176, v222
	ds_bpermute_b32 v225, v176, v224
	s_waitcnt lgkmcnt(7)
	v_add_f32_e32 v210, v210, v211
	s_waitcnt lgkmcnt(6)
	v_add_f32_e32 v212, v212, v213
	s_waitcnt lgkmcnt(5)
	v_add_f32_e32 v214, v214, v215
	s_waitcnt lgkmcnt(4)
	v_add_f32_e32 v216, v216, v217
	s_waitcnt lgkmcnt(3)
	v_add_f32_e32 v218, v218, v219
	s_waitcnt lgkmcnt(2)
	v_add_f32_e32 v220, v220, v221
	s_waitcnt lgkmcnt(1)
	v_add_f32_e32 v222, v222, v223
	s_waitcnt lgkmcnt(0)
	v_add_f32_e32 v224, v224, v225
	v_fmamk_f32 v210, v210, 0x3a800000, v228
	v_fmamk_f32 v212, v212, 0x3a800000, v228
	v_fmamk_f32 v214, v214, 0x3a800000, v228
	v_fmamk_f32 v216, v216, 0x3a800000, v228
	v_fmamk_f32 v218, v218, 0x3a800000, v228
	v_fmamk_f32 v220, v220, 0x3a800000, v228
	v_fmamk_f32 v222, v222, 0x3a800000, v228
	v_fmamk_f32 v224, v224, 0x3a800000, v228
	v_rsq_f32_e32 v210, v210
	v_rsq_f32_e32 v212, v212
	v_rsq_f32_e32 v214, v214
	v_rsq_f32_e32 v216, v216
	v_rsq_f32_e32 v218, v218
	v_rsq_f32_e32 v220, v220
	v_rsq_f32_e32 v222, v222
	v_rsq_f32_e32 v224, v224
	v_pk_mul_f32 v[0:1], v[0:1], v[210:211] op_sel_hi:[1,0]
	v_pk_mul_f32 v[2:3], v[2:3], v[210:211] op_sel_hi:[1,0]
	v_pk_fma_f32 v[0:1], v[0:1], v[178:179], v[194:195]
	v_pk_fma_f32 v[2:3], v[2:3], v[180:181], v[196:197]
	v_cvt_pk_bf16_f32 v0, v0, v1
	v_cvt_pk_bf16_f32 v1, v2, v3
	global_store_dwordx2 v227, v[0:1], s[56:57]
	v_pk_mul_f32 v[4:5], v[4:5], v[210:211] op_sel_hi:[1,0]
	v_pk_mul_f32 v[6:7], v[6:7], v[210:211] op_sel_hi:[1,0]
	v_pk_fma_f32 v[4:5], v[4:5], v[182:183], v[198:199]
	v_pk_fma_f32 v[6:7], v[6:7], v[184:185], v[200:201]
	v_cvt_pk_bf16_f32 v4, v4, v5
	v_cvt_pk_bf16_f32 v5, v6, v7
	global_store_dwordx2 v227, v[4:5], s[56:57] offset:512
	v_pk_mul_f32 v[8:9], v[8:9], v[210:211] op_sel_hi:[1,0]
	v_pk_mul_f32 v[10:11], v[10:11], v[210:211] op_sel_hi:[1,0]
	v_pk_fma_f32 v[8:9], v[8:9], v[186:187], v[202:203]
	v_pk_fma_f32 v[10:11], v[10:11], v[188:189], v[204:205]
	v_cvt_pk_bf16_f32 v8, v8, v9
	v_cvt_pk_bf16_f32 v9, v10, v11
	global_store_dwordx2 v227, v[8:9], s[56:57] offset:1024
	v_pk_mul_f32 v[12:13], v[12:13], v[210:211] op_sel_hi:[1,0]
	v_pk_mul_f32 v[14:15], v[14:15], v[210:211] op_sel_hi:[1,0]
	v_pk_fma_f32 v[12:13], v[12:13], v[190:191], v[206:207]
	v_pk_fma_f32 v[14:15], v[14:15], v[192:193], v[208:209]
	v_cvt_pk_bf16_f32 v12, v12, v13
	v_cvt_pk_bf16_f32 v13, v14, v15
	global_store_dwordx2 v227, v[12:13], s[56:57] offset:1536
	s_add_u32 s56, s56, 0x4000
	s_addc_u32 s57, s57, 0
	v_pk_mul_f32 v[16:17], v[16:17], v[212:213] op_sel_hi:[1,0]
	v_pk_mul_f32 v[18:19], v[18:19], v[212:213] op_sel_hi:[1,0]
	v_pk_fma_f32 v[16:17], v[16:17], v[178:179], v[194:195]
	v_pk_fma_f32 v[18:19], v[18:19], v[180:181], v[196:197]
	v_cvt_pk_bf16_f32 v16, v16, v17
	v_cvt_pk_bf16_f32 v17, v18, v19
	global_store_dwordx2 v227, v[16:17], s[56:57]
	v_pk_mul_f32 v[20:21], v[20:21], v[212:213] op_sel_hi:[1,0]
	v_pk_mul_f32 v[22:23], v[22:23], v[212:213] op_sel_hi:[1,0]
	v_pk_fma_f32 v[20:21], v[20:21], v[182:183], v[198:199]
	v_pk_fma_f32 v[22:23], v[22:23], v[184:185], v[200:201]
	v_cvt_pk_bf16_f32 v20, v20, v21
	v_cvt_pk_bf16_f32 v21, v22, v23
	global_store_dwordx2 v227, v[20:21], s[56:57] offset:512
	v_pk_mul_f32 v[24:25], v[24:25], v[212:213] op_sel_hi:[1,0]
	v_pk_mul_f32 v[26:27], v[26:27], v[212:213] op_sel_hi:[1,0]
	v_pk_fma_f32 v[24:25], v[24:25], v[186:187], v[202:203]
	v_pk_fma_f32 v[26:27], v[26:27], v[188:189], v[204:205]
	v_cvt_pk_bf16_f32 v24, v24, v25
	v_cvt_pk_bf16_f32 v25, v26, v27
	global_store_dwordx2 v227, v[24:25], s[56:57] offset:1024
	v_pk_mul_f32 v[28:29], v[28:29], v[212:213] op_sel_hi:[1,0]
	v_pk_mul_f32 v[30:31], v[30:31], v[212:213] op_sel_hi:[1,0]
	v_pk_fma_f32 v[28:29], v[28:29], v[190:191], v[206:207]
	v_pk_fma_f32 v[30:31], v[30:31], v[192:193], v[208:209]
	v_cvt_pk_bf16_f32 v28, v28, v29
	v_cvt_pk_bf16_f32 v29, v30, v31
	global_store_dwordx2 v227, v[28:29], s[56:57] offset:1536
	s_add_u32 s56, s56, 0x4000
	s_addc_u32 s57, s57, 0
	v_pk_mul_f32 v[32:33], v[32:33], v[214:215] op_sel_hi:[1,0]
	v_pk_mul_f32 v[34:35], v[34:35], v[214:215] op_sel_hi:[1,0]
	v_pk_fma_f32 v[32:33], v[32:33], v[178:179], v[194:195]
	v_pk_fma_f32 v[34:35], v[34:35], v[180:181], v[196:197]
	v_cvt_pk_bf16_f32 v32, v32, v33
	v_cvt_pk_bf16_f32 v33, v34, v35
	global_store_dwordx2 v227, v[32:33], s[56:57]
	v_pk_mul_f32 v[36:37], v[36:37], v[214:215] op_sel_hi:[1,0]
	v_pk_mul_f32 v[38:39], v[38:39], v[214:215] op_sel_hi:[1,0]
	v_pk_fma_f32 v[36:37], v[36:37], v[182:183], v[198:199]
	v_pk_fma_f32 v[38:39], v[38:39], v[184:185], v[200:201]
	v_cvt_pk_bf16_f32 v36, v36, v37
	v_cvt_pk_bf16_f32 v37, v38, v39
	global_store_dwordx2 v227, v[36:37], s[56:57] offset:512
	v_pk_mul_f32 v[40:41], v[40:41], v[214:215] op_sel_hi:[1,0]
	v_pk_mul_f32 v[42:43], v[42:43], v[214:215] op_sel_hi:[1,0]
	v_pk_fma_f32 v[40:41], v[40:41], v[186:187], v[202:203]
	v_pk_fma_f32 v[42:43], v[42:43], v[188:189], v[204:205]
	v_cvt_pk_bf16_f32 v40, v40, v41
	v_cvt_pk_bf16_f32 v41, v42, v43
	global_store_dwordx2 v227, v[40:41], s[56:57] offset:1024
	v_pk_mul_f32 v[44:45], v[44:45], v[214:215] op_sel_hi:[1,0]
	v_pk_mul_f32 v[46:47], v[46:47], v[214:215] op_sel_hi:[1,0]
	v_pk_fma_f32 v[44:45], v[44:45], v[190:191], v[206:207]
	v_pk_fma_f32 v[46:47], v[46:47], v[192:193], v[208:209]
	v_cvt_pk_bf16_f32 v44, v44, v45
	v_cvt_pk_bf16_f32 v45, v46, v47
	global_store_dwordx2 v227, v[44:45], s[56:57] offset:1536
	s_add_u32 s56, s56, 0x4000
	s_addc_u32 s57, s57, 0
	v_pk_mul_f32 v[48:49], v[48:49], v[216:217] op_sel_hi:[1,0]
	v_pk_mul_f32 v[50:51], v[50:51], v[216:217] op_sel_hi:[1,0]
	v_pk_fma_f32 v[48:49], v[48:49], v[178:179], v[194:195]
	v_pk_fma_f32 v[50:51], v[50:51], v[180:181], v[196:197]
	v_cvt_pk_bf16_f32 v48, v48, v49
	v_cvt_pk_bf16_f32 v49, v50, v51
	global_store_dwordx2 v227, v[48:49], s[56:57]
	v_pk_mul_f32 v[52:53], v[52:53], v[216:217] op_sel_hi:[1,0]
	v_pk_mul_f32 v[54:55], v[54:55], v[216:217] op_sel_hi:[1,0]
	v_pk_fma_f32 v[52:53], v[52:53], v[182:183], v[198:199]
	v_pk_fma_f32 v[54:55], v[54:55], v[184:185], v[200:201]
	v_cvt_pk_bf16_f32 v52, v52, v53
	v_cvt_pk_bf16_f32 v53, v54, v55
	global_store_dwordx2 v227, v[52:53], s[56:57] offset:512
	v_pk_mul_f32 v[56:57], v[56:57], v[216:217] op_sel_hi:[1,0]
	v_pk_mul_f32 v[58:59], v[58:59], v[216:217] op_sel_hi:[1,0]
	v_pk_fma_f32 v[56:57], v[56:57], v[186:187], v[202:203]
	v_pk_fma_f32 v[58:59], v[58:59], v[188:189], v[204:205]
	v_cvt_pk_bf16_f32 v56, v56, v57
	v_cvt_pk_bf16_f32 v57, v58, v59
	global_store_dwordx2 v227, v[56:57], s[56:57] offset:1024
	v_pk_mul_f32 v[60:61], v[60:61], v[216:217] op_sel_hi:[1,0]
	v_pk_mul_f32 v[62:63], v[62:63], v[216:217] op_sel_hi:[1,0]
	v_pk_fma_f32 v[60:61], v[60:61], v[190:191], v[206:207]
	v_pk_fma_f32 v[62:63], v[62:63], v[192:193], v[208:209]
	v_cvt_pk_bf16_f32 v60, v60, v61
	v_cvt_pk_bf16_f32 v61, v62, v63
	global_store_dwordx2 v227, v[60:61], s[56:57] offset:1536
	s_add_u32 s56, s56, 0x4000
	s_addc_u32 s57, s57, 0
	v_pk_mul_f32 v[64:65], v[64:65], v[218:219] op_sel_hi:[1,0]
	v_pk_mul_f32 v[66:67], v[66:67], v[218:219] op_sel_hi:[1,0]
	v_pk_fma_f32 v[64:65], v[64:65], v[178:179], v[194:195]
	v_pk_fma_f32 v[66:67], v[66:67], v[180:181], v[196:197]
	v_cvt_pk_bf16_f32 v64, v64, v65
	v_cvt_pk_bf16_f32 v65, v66, v67
	global_store_dwordx2 v227, v[64:65], s[56:57]
	v_pk_mul_f32 v[68:69], v[68:69], v[218:219] op_sel_hi:[1,0]
	v_pk_mul_f32 v[70:71], v[70:71], v[218:219] op_sel_hi:[1,0]
	v_pk_fma_f32 v[68:69], v[68:69], v[182:183], v[198:199]
	v_pk_fma_f32 v[70:71], v[70:71], v[184:185], v[200:201]
	v_cvt_pk_bf16_f32 v68, v68, v69
	v_cvt_pk_bf16_f32 v69, v70, v71
	global_store_dwordx2 v227, v[68:69], s[56:57] offset:512
	v_pk_mul_f32 v[72:73], v[72:73], v[218:219] op_sel_hi:[1,0]
	v_pk_mul_f32 v[74:75], v[74:75], v[218:219] op_sel_hi:[1,0]
	v_pk_fma_f32 v[72:73], v[72:73], v[186:187], v[202:203]
	v_pk_fma_f32 v[74:75], v[74:75], v[188:189], v[204:205]
	v_cvt_pk_bf16_f32 v72, v72, v73
	v_cvt_pk_bf16_f32 v73, v74, v75
	global_store_dwordx2 v227, v[72:73], s[56:57] offset:1024
	v_pk_mul_f32 v[76:77], v[76:77], v[218:219] op_sel_hi:[1,0]
	v_pk_mul_f32 v[78:79], v[78:79], v[218:219] op_sel_hi:[1,0]
	v_pk_fma_f32 v[76:77], v[76:77], v[190:191], v[206:207]
	v_pk_fma_f32 v[78:79], v[78:79], v[192:193], v[208:209]
	v_cvt_pk_bf16_f32 v76, v76, v77
	v_cvt_pk_bf16_f32 v77, v78, v79
	global_store_dwordx2 v227, v[76:77], s[56:57] offset:1536
	s_add_u32 s56, s56, 0x4000
	s_addc_u32 s57, s57, 0
	v_pk_mul_f32 v[80:81], v[80:81], v[220:221] op_sel_hi:[1,0]
	v_pk_mul_f32 v[82:83], v[82:83], v[220:221] op_sel_hi:[1,0]
	v_pk_fma_f32 v[80:81], v[80:81], v[178:179], v[194:195]
	v_pk_fma_f32 v[82:83], v[82:83], v[180:181], v[196:197]
	v_cvt_pk_bf16_f32 v80, v80, v81
	v_cvt_pk_bf16_f32 v81, v82, v83
	global_store_dwordx2 v227, v[80:81], s[56:57]
	v_pk_mul_f32 v[84:85], v[84:85], v[220:221] op_sel_hi:[1,0]
	v_pk_mul_f32 v[86:87], v[86:87], v[220:221] op_sel_hi:[1,0]
	v_pk_fma_f32 v[84:85], v[84:85], v[182:183], v[198:199]
	v_pk_fma_f32 v[86:87], v[86:87], v[184:185], v[200:201]
	v_cvt_pk_bf16_f32 v84, v84, v85
	v_cvt_pk_bf16_f32 v85, v86, v87
	global_store_dwordx2 v227, v[84:85], s[56:57] offset:512
	v_pk_mul_f32 v[88:89], v[88:89], v[220:221] op_sel_hi:[1,0]
	v_pk_mul_f32 v[90:91], v[90:91], v[220:221] op_sel_hi:[1,0]
	v_pk_fma_f32 v[88:89], v[88:89], v[186:187], v[202:203]
	v_pk_fma_f32 v[90:91], v[90:91], v[188:189], v[204:205]
	v_cvt_pk_bf16_f32 v88, v88, v89
	v_cvt_pk_bf16_f32 v89, v90, v91
	global_store_dwordx2 v227, v[88:89], s[56:57] offset:1024
	v_pk_mul_f32 v[92:93], v[92:93], v[220:221] op_sel_hi:[1,0]
	v_pk_mul_f32 v[94:95], v[94:95], v[220:221] op_sel_hi:[1,0]
	v_pk_fma_f32 v[92:93], v[92:93], v[190:191], v[206:207]
	v_pk_fma_f32 v[94:95], v[94:95], v[192:193], v[208:209]
	v_cvt_pk_bf16_f32 v92, v92, v93
	v_cvt_pk_bf16_f32 v93, v94, v95
	global_store_dwordx2 v227, v[92:93], s[56:57] offset:1536
	s_add_u32 s56, s56, 0x4000
	s_addc_u32 s57, s57, 0
	v_pk_mul_f32 v[134:135], v[134:135], v[222:223] op_sel_hi:[1,0]
	v_pk_mul_f32 v[136:137], v[136:137], v[222:223] op_sel_hi:[1,0]
	v_pk_fma_f32 v[134:135], v[134:135], v[178:179], v[194:195]
	v_pk_fma_f32 v[136:137], v[136:137], v[180:181], v[196:197]
	v_cvt_pk_bf16_f32 v134, v134, v135
	v_cvt_pk_bf16_f32 v135, v136, v137
	global_store_dwordx2 v227, v[134:135], s[56:57]
	v_pk_mul_f32 v[138:139], v[138:139], v[222:223] op_sel_hi:[1,0]
	v_pk_mul_f32 v[140:141], v[140:141], v[222:223] op_sel_hi:[1,0]
	v_pk_fma_f32 v[138:139], v[138:139], v[182:183], v[198:199]
	v_pk_fma_f32 v[140:141], v[140:141], v[184:185], v[200:201]
	v_cvt_pk_bf16_f32 v138, v138, v139
	v_cvt_pk_bf16_f32 v139, v140, v141
	global_store_dwordx2 v227, v[138:139], s[56:57] offset:512
	v_pk_mul_f32 v[142:143], v[142:143], v[222:223] op_sel_hi:[1,0]
	v_pk_mul_f32 v[144:145], v[144:145], v[222:223] op_sel_hi:[1,0]
	v_pk_fma_f32 v[142:143], v[142:143], v[186:187], v[202:203]
	v_pk_fma_f32 v[144:145], v[144:145], v[188:189], v[204:205]
	v_cvt_pk_bf16_f32 v142, v142, v143
	v_cvt_pk_bf16_f32 v143, v144, v145
	global_store_dwordx2 v227, v[142:143], s[56:57] offset:1024
	v_pk_mul_f32 v[146:147], v[146:147], v[222:223] op_sel_hi:[1,0]
	v_pk_mul_f32 v[148:149], v[148:149], v[222:223] op_sel_hi:[1,0]
	v_pk_fma_f32 v[146:147], v[146:147], v[190:191], v[206:207]
	v_pk_fma_f32 v[148:149], v[148:149], v[192:193], v[208:209]
	v_cvt_pk_bf16_f32 v146, v146, v147
	v_cvt_pk_bf16_f32 v147, v148, v149
	global_store_dwordx2 v227, v[146:147], s[56:57] offset:1536
	s_add_u32 s56, s56, 0x4000
	s_addc_u32 s57, s57, 0
	v_pk_mul_f32 v[150:151], v[150:151], v[224:225] op_sel_hi:[1,0]
	v_pk_mul_f32 v[152:153], v[152:153], v[224:225] op_sel_hi:[1,0]
	v_pk_fma_f32 v[150:151], v[150:151], v[178:179], v[194:195]
	v_pk_fma_f32 v[152:153], v[152:153], v[180:181], v[196:197]
	v_cvt_pk_bf16_f32 v150, v150, v151
	v_cvt_pk_bf16_f32 v151, v152, v153
	global_store_dwordx2 v227, v[150:151], s[56:57]
	v_pk_mul_f32 v[154:155], v[154:155], v[224:225] op_sel_hi:[1,0]
	v_pk_mul_f32 v[156:157], v[156:157], v[224:225] op_sel_hi:[1,0]
	v_pk_fma_f32 v[154:155], v[154:155], v[182:183], v[198:199]
	v_pk_fma_f32 v[156:157], v[156:157], v[184:185], v[200:201]
	v_cvt_pk_bf16_f32 v154, v154, v155
	v_cvt_pk_bf16_f32 v155, v156, v157
	global_store_dwordx2 v227, v[154:155], s[56:57] offset:512
	v_pk_mul_f32 v[158:159], v[158:159], v[224:225] op_sel_hi:[1,0]
	v_pk_mul_f32 v[160:161], v[160:161], v[224:225] op_sel_hi:[1,0]
	v_pk_fma_f32 v[158:159], v[158:159], v[186:187], v[202:203]
	v_pk_fma_f32 v[160:161], v[160:161], v[188:189], v[204:205]
	v_cvt_pk_bf16_f32 v158, v158, v159
	v_cvt_pk_bf16_f32 v159, v160, v161
	global_store_dwordx2 v227, v[158:159], s[56:57] offset:1024
	v_pk_mul_f32 v[162:163], v[162:163], v[224:225] op_sel_hi:[1,0]
	v_pk_mul_f32 v[164:165], v[164:165], v[224:225] op_sel_hi:[1,0]
	v_pk_fma_f32 v[162:163], v[162:163], v[190:191], v[206:207]
	v_pk_fma_f32 v[164:165], v[164:165], v[192:193], v[208:209]
	v_cvt_pk_bf16_f32 v162, v162, v163
	v_cvt_pk_bf16_f32 v163, v164, v165
	global_store_dwordx2 v227, v[162:163], s[56:57] offset:1536

.LBB0_2060:
	global_load_dword v1, v0, s[8:9] sc1
	s_mov_b64 s[10:11], -1
	s_waitcnt vmcnt(0)
	v_cmp_lt_u32_e32 vcc, 3, v1
	s_cbranch_vccnz .LBB0_2059
	s_sleep 2
	global_load_dword v1, v0, s[8:9] sc1
	s_waitcnt vmcnt(0)
	v_cmp_gt_u32_e32 vcc, 4, v1
	s_cbranch_vccz .LBB0_2059
	s_sleep 2
	global_load_dword v1, v0, s[8:9] sc1
	s_waitcnt vmcnt(0)
	v_cmp_gt_u32_e32 vcc, 4, v1
	s_cbranch_vccz .LBB0_2059
	s_sleep 2
	global_load_dword v1, v0, s[8:9] sc1
	s_waitcnt vmcnt(0)
	v_cmp_gt_u32_e32 vcc, 4, v1
	s_cbranch_vccz .LBB0_2059
	s_sleep 2
	global_load_dword v1, v0, s[8:9] sc1
	s_waitcnt vmcnt(0)
	v_cmp_gt_u32_e32 vcc, 4, v1
	s_cbranch_vccz .LBB0_2059
	s_add_i32 s3, s3, -5
	s_cmp_eq_u32 s3, 0
	s_cselect_b64 s[10:11], -1, 0
	s_sleep 2
	s_branch .LBB0_2059
.LBB0_2066:
	s_waitcnt vmcnt(0)
.LBB0_2067:
	s_or_b64 exec, exec, s[6:7]
	s_sext_i32_i8 s3, s20
	s_lshl_b32 s2, s2, 8
	s_lshl_b32 s3, s3, 6
	s_add_i32 s20, s2, s3
	s_add_u32 s18, s16, 0x56bc000
	s_addc_u32 s19, s17, 0
	s_sub_i32 s6, s21, s23
	s_lshl_b32 s7, s22, 5
	s_sub_i32 s6, s6, s7
	s_sext_i32_i8 s6, s6
	s_lshl_b32 s6, s6, 8
	v_mov_b32_e32 v1, v170
	s_lshl_b32 s2, s22, 11
	s_add_i32 s3, s3, s6
	s_waitcnt lgkmcnt(0)
	s_barrier
	s_load_dwordx2 s[52:53], s[0:1], 0xe8
	s_load_dwordx4 s[68:71], s[0:1], 0xd8
	s_mov_b32 s66, s20
	v_readfirstlane_b32 s60, v170
	v_and_b32_e32 v194, 63, v170
	v_lshrrev_b32_e32 v195, 6, v170
	v_and_b32_e32 v196, 15, v194
	v_lshrrev_b32_e32 v194, 4, v194
	v_and_b32_e32 v197, 3, v195
	v_lshrrev_b32_e32 v195, 2, v195
	v_lshl_add_u32 v196, v195, 6, v196
	v_lshl_add_u32 v197, v197, 5, 0
	v_lshl_add_u32 v197, v194, 2, v197
	s_lshr_b32 s64, s66, 8
	s_lshr_b32 s65, s66, 6
	s_and_b32 s65, s65, 3
	s_lshl_b32 s67, s65, 8
	v_add_u32_e32 v197, s67, v197
	s_waitcnt lgkmcnt(0)
	s_lshl_b32 s61, s64, 12
	s_add_u32 s62, s52, s61
	s_addc_u32 s63, s53, 0
	s_add_u32 s62, s62, 0xc0000
	s_addc_u32 s63, s63, 0
	s_cmp_lt_u32 s60, 256
	s_cbranch_scc0 .Lf2p16_nor
	v_lshlrev_b32_e32 v190, 2, v170
	global_load_dword v192, v190, s[62:63] sc1
	global_load_dword v193, v190, s[62:63] offset:1024 sc1
	global_load_dword v198, v190, s[62:63] offset:2048 sc1
	global_load_dword v199, v190, s[62:63] offset:3072 sc1
	v_mov_b32_e32 v191, 0x358637bd
	s_waitcnt vmcnt(0)
	v_add_f32_e32 v192, v192, v193
	v_add_f32_e32 v198, v198, v199
	v_add_f32_e32 v192, v192, v198
	v_fmamk_f32 v192, v192, 0x3a800000, v191
	v_rsq_f32_e32 v192, v192
	v_add_u32_e32 v191, 0x21000, v190
	s_nop 0
	ds_write_b32 v191, v192
